# window/slc unit epilogues: partial-buffer loads issued together; rescale-trigger test shortened (no exec save, no re-ballot)
# baseline (speedup 1.0000x reference)
; DI void qk_acc(lptr Kt, const bf16x8 (&qf)[4], f32x16& s0, f32x16& s1, int lane) {
;     const int i = lane & 31, hi = lane >> 5;
;     const int krow = (i & 19) | ((i & 4) << 1) | ((i & 8) >> 1);
;     lptr kp = Kt + krow * KPB + hi * 16;
;     bf16x8 a0[4], a1[4];
; #pragma unroll
;     for (int d0 = 0; d0 < 4; ++d0) { a0[d0] = *(LAS bf16x8*)(kp + d0 * 32); a1[d0] = *(LAS bf16x8*)(kp + 32 * KPB + d0 * 32); }
;     __builtin_amdgcn_s_setprio(1);
; template <int MODE>
; DI void bias_init(f32x16& s0, f32x16& s1, const TP& tp, float fbm, int hi) {
; #pragma unroll
;     for (int r = 0; r < 16; ++r) {
;         const int kvc = 16 * (r >> 3) + (r & 7);
;         if (MODE == 0) { s0[r] = __builtin_fmaf(-L2E, tp.cs[kvc + 8 * hi], fbm); s1[r] = __builtin_fmaf(-L2E, tp.cs[kvc + 32 + 8 * hi], fbm); }
;         else { s0[r] = __builtin_fmaf(tp.sl, (float)kvc, fbm); s1[r] = __builtin_fmaf(tp.sl, (float)(kvc + 32), fbm); }
;     }
; }
; DI float max3_asm(float a, float b, float c) { float r; asm("v_max3_f32 %0, %1, %2, %3" : "=v"(r) : "v"(a), "v"(b), "v"(c)); return r; }
; template <bool MASK>
; DI float mask_rowmax(f32x16& s0, f32x16& s1, const TP& tp) {
;     if (MASK) {
; #pragma unroll
;         for (int r = 0; r < 16; ++r) {
;             const int kvc = 16 * (r >> 3) + (r & 7);
;             const bool v0 = tp.sel && (kvc <= tp.lim) && (kvc > tp.lim2), v1 = tp.sel && (kvc + 32 <= tp.lim) && (kvc + 32 > tp.lim2);
;             s0[r] = v0 ? s0[r] : -1e30f; s1[r] = v1 ? s1[r] : -1e30f;
;         }
;     }
;     const float seed = __builtin_fminf(s0[15], s1[15]);
;     float ma = seed, mb = seed;
; #pragma unroll
;     for (int r = 0; r < 16; r += 2) { ma = max3_asm(ma, s0[r], s1[r]); mb = max3_asm(mb, s0[r + 1], s1[r + 1]); }
;     const float mx = fmaxf(ma, mb);
;     return fmaxf(mx, __shfl_xor(mx, 32));
; }
; template <int MODE, bool MASK, bool WITH_O>
; DI void attn_tile_t(lptr Kt, lptr Vt, const bf16x8 (&qf)[4], f32x16& o0, f32x16& o1, RowState& rs, const TP& tp, int lane) {
;     const int hi = lane >> 5;
;     f32x16 s0, s1;
;     bias_init<MODE>(s0, s1, tp, tp.fb - rs.mref, hi);
;     qk_acc(Kt, qf, s0, s1, lane);
;     const float mx = mask_rowmax<MASK>(s0, s1, tp);
;     const bool was = rs.seen; rs.seen = was || (mx > -1e29f);
;     const bool trig = (mx > 8.f) || (!was && mx > -1e29f && mx < -8.f);
;     if (__builtin_expect(__any(trig), 0)) {
.LBB0_493:
	s_lshl_b32 s2, s55, 8
	s_add_i32 s26, s2, 0
	s_mul_i32 s2, s55, 0x2300
	s_add_i32 s56, s26, s2
	s_mov_b64 s[2:3], -1
	s_cmp_le_i32 s31, s42
	v_sub_f32_e32 v156, v157, v160
	v_add3_u32 v161, s56, v131, v133
	v_lshl_add_u32 v162, v126, 2, s26
	s_cbranch_scc0 .LBB0_498
	ds_read_b128 v[34:37], v162 offset:36992
	ds_read_b128 v[38:41], v162 offset:36864
	ds_read_b128 v[42:45], v162 offset:36880
	ds_read_b128 v[46:49], v162 offset:37008
	ds_read_b128 v[50:53], v162 offset:36928
	ds_read_b128 v[54:57], v162 offset:37056
	ds_read_b128 v[58:61], v162 offset:36944
	ds_read_b128 v[62:65], v162 offset:37072
	s_waitcnt lgkmcnt(5)
	v_pk_fma_f32 v[88:89], v[44:45], s[80:81], v[156:157] op_sel_hi:[1,0,0]
	s_waitcnt lgkmcnt(3)
	v_pk_fma_f32 v[92:93], v[52:53], s[80:81], v[156:157] op_sel_hi:[1,0,0]
	v_pk_fma_f32 v[84:85], v[40:41], s[80:81], v[156:157] op_sel_hi:[1,0,0]
	s_waitcnt lgkmcnt(1)
	v_pk_fma_f32 v[96:97], v[60:61], s[80:81], v[156:157] op_sel_hi:[1,0,0]
	v_pk_fma_f32 v[94:95], v[58:59], s[80:81], v[156:157] op_sel_hi:[1,0,0]
	v_pk_fma_f32 v[90:91], v[50:51], s[80:81], v[156:157] op_sel_hi:[1,0,0]
	v_pk_fma_f32 v[86:87], v[42:43], s[80:81], v[156:157] op_sel_hi:[1,0,0]
	v_pk_fma_f32 v[82:83], v[38:39], s[80:81], v[156:157] op_sel_hi:[1,0,0]
	s_waitcnt lgkmcnt(0)
	v_pk_fma_f32 v[80:81], v[64:65], s[80:81], v[156:157] op_sel_hi:[1,0,0]
	v_pk_fma_f32 v[76:77], v[56:57], s[80:81], v[156:157] op_sel_hi:[1,0,0]
	v_pk_fma_f32 v[72:73], v[48:49], s[80:81], v[156:157] op_sel_hi:[1,0,0]
	v_pk_fma_f32 v[68:69], v[36:37], s[80:81], v[156:157] op_sel_hi:[1,0,0]
	v_pk_fma_f32 v[78:79], v[62:63], s[80:81], v[156:157] op_sel_hi:[1,0,0]
	v_pk_fma_f32 v[74:75], v[54:55], s[80:81], v[156:157] op_sel_hi:[1,0,0]
	v_pk_fma_f32 v[70:71], v[46:47], s[80:81], v[156:157] op_sel_hi:[1,0,0]
	v_pk_fma_f32 v[66:67], v[34:35], s[80:81], v[156:157] op_sel_hi:[1,0,0]
	ds_read_b128 v[34:37], v161 offset:4608
	ds_read_b128 v[38:41], v161
	ds_read_b128 v[42:45], v161 offset:32
	ds_read_b128 v[46:49], v161 offset:4640
	ds_read_b128 v[50:53], v161 offset:64
	ds_read_b128 v[54:57], v161 offset:4672
	ds_read_b128 v[58:61], v161 offset:96
	ds_read_b128 v[62:65], v161 offset:4704
	s_setprio 1
	s_waitcnt lgkmcnt(6)
	v_mfma_f32_32x32x16_bf16 v[82:97], v[38:41], v[98:101], v[82:97]
	v_mfma_f32_32x32x16_bf16 v[66:81], v[34:37], v[98:101], v[66:81]
	s_waitcnt lgkmcnt(5)
	v_mfma_f32_32x32x16_bf16 v[82:97], v[42:45], v[102:105], v[82:97]
	s_waitcnt lgkmcnt(4)
	v_mfma_f32_32x32x16_bf16 v[66:81], v[46:49], v[102:105], v[66:81]
	s_waitcnt lgkmcnt(3)
	v_mfma_f32_32x32x16_bf16 v[82:97], v[50:53], v[106:109], v[82:97]
	s_waitcnt lgkmcnt(2)
	v_mfma_f32_32x32x16_bf16 v[66:81], v[54:57], v[106:109], v[66:81]
	s_waitcnt lgkmcnt(1)
	v_mfma_f32_32x32x16_bf16 v[82:97], v[58:61], v[110:113], v[82:97]
	s_waitcnt lgkmcnt(0)
	v_mfma_f32_32x32x16_bf16 v[66:81], v[62:65], v[110:113], v[66:81]
	s_setprio 0
	s_nop 10
	v_max_f32_e32 v34, v81, v81
	v_max_f32_e32 v35, v97, v97
	v_min_f32_e32 v34, v35, v34
	v_max3_f32 v35, v34, v82, v66
	v_max3_f32 v34, v34, v83, v67
	v_and_b32_e32 v36, 64, v209
	v_max3_f32 v35, v35, v84, v68
	v_max3_f32 v34, v34, v85, v69
	v_add_u32_e32 v36, 64, v36
	v_max3_f32 v35, v35, v86, v70
	v_max3_f32 v34, v34, v87, v71
	s_mov_b32 s2, 0xefa18f08
	v_max3_f32 v35, v35, v88, v72
	v_max3_f32 v34, v34, v89, v73
	s_mov_b64 s[28:29], -1
	v_max3_f32 v35, v35, v90, v74
	v_max3_f32 v34, v34, v91, v75
	s_nop 0
	v_max3_f32 v35, v35, v92, v76
	v_max3_f32 v34, v34, v93, v77
	s_nop 0
	v_max3_f32 v35, v35, v94, v78
	v_max3_f32 v34, v34, v95, v79
	s_nop 0
	v_max3_f32 v35, v35, v96, v80
	v_max3_f32 v34, v34, v97, v81
	s_nop 0
	v_max_f32_e32 v34, v34, v34
	v_max_f32_e32 v35, v35, v35
	v_max_f32_e32 v34, v35, v34
	v_xor_b32_e32 v35, 32, v209
	v_cmp_lt_i32_e32 vcc, v35, v36
	s_nop 1
	v_cndmask_b32_e32 v35, v209, v35, vcc
	v_lshlrev_b32_e32 v35, 2, v35
	ds_bpermute_b32 v35, v35, v34
	s_waitcnt lgkmcnt(0)
	v_max_f32_e32 v35, v35, v35
	v_max_f32_e32 v165, v34, v35
	v_cmp_lt_f32_e64 s[26:27], s2, v165
	s_mov_b32 s2, 0x41000000
	v_cmp_lt_f32_e32 vcc, s2, v165
	s_mov_b32 s28, 0xc1000000
	v_cmp_gt_f32_e64 s[28:29], s28, v165
	s_and_b64 s[28:29], s[28:29], s[26:27]
	s_andn2_b64 s[28:29], s[28:29], s[22:23]
	s_or_b64 s[28:29], s[28:29], vcc
	s_and_b64 vcc, exec, s[28:29]
	v_mov_b32_e32 v163, v160
	v_mov_b32_e32 v164, v159
	s_cbranch_vccnz .LBB0_514

; DI void qk_acc(lptr Kt, const bf16x8 (&qf)[4], f32x16& s0, f32x16& s1, int lane) {
;     const int i = lane & 31, hi = lane >> 5;
;     const int krow = (i & 19) | ((i & 4) << 1) | ((i & 8) >> 1);
;     lptr kp = Kt + krow * KPB + hi * 16;
;     bf16x8 a0[4], a1[4];
; #pragma unroll
;     for (int d0 = 0; d0 < 4; ++d0) { a0[d0] = *(LAS bf16x8*)(kp + d0 * 32); a1[d0] = *(LAS bf16x8*)(kp + 32 * KPB + d0 * 32); }
;     __builtin_amdgcn_s_setprio(1);
; template <int MODE>
; DI void bias_init(f32x16& s0, f32x16& s1, const TP& tp, float fbm, int hi) {
; #pragma unroll
;     for (int r = 0; r < 16; ++r) {
;         const int kvc = 16 * (r >> 3) + (r & 7);
;         if (MODE == 0) { s0[r] = __builtin_fmaf(-L2E, tp.cs[kvc + 8 * hi], fbm); s1[r] = __builtin_fmaf(-L2E, tp.cs[kvc + 32 + 8 * hi], fbm); }
;         else { s0[r] = __builtin_fmaf(tp.sl, (float)kvc, fbm); s1[r] = __builtin_fmaf(tp.sl, (float)(kvc + 32), fbm); }
;     }
; }
; DI float max3_asm(float a, float b, float c) { float r; asm("v_max3_f32 %0, %1, %2, %3" : "=v"(r) : "v"(a), "v"(b), "v"(c)); return r; }
; template <bool MASK>
; DI float mask_rowmax(f32x16& s0, f32x16& s1, const TP& tp) {
;     if (MASK) {
; #pragma unroll
;         for (int r = 0; r < 16; ++r) {
;             const int kvc = 16 * (r >> 3) + (r & 7);
;             const bool v0 = tp.sel && (kvc <= tp.lim) && (kvc > tp.lim2), v1 = tp.sel && (kvc + 32 <= tp.lim) && (kvc + 32 > tp.lim2);
;             s0[r] = v0 ? s0[r] : -1e30f; s1[r] = v1 ? s1[r] : -1e30f;
;         }
;     }
;     const float seed = __builtin_fminf(s0[15], s1[15]);
;     float ma = seed, mb = seed;
; #pragma unroll
;     for (int r = 0; r < 16; r += 2) { ma = max3_asm(ma, s0[r], s1[r]); mb = max3_asm(mb, s0[r + 1], s1[r + 1]); }
;     const float mx = fmaxf(ma, mb);
;     return fmaxf(mx, __shfl_xor(mx, 32));
; }
; template <int MODE, bool MASK, bool WITH_O>
; DI void attn_tile_t(lptr Kt, lptr Vt, const bf16x8 (&qf)[4], f32x16& o0, f32x16& o1, RowState& rs, const TP& tp, int lane) {
;     const int hi = lane >> 5;
;     f32x16 s0, s1;
;     bias_init<MODE>(s0, s1, tp, tp.fb - rs.mref, hi);
;     qk_acc(Kt, qf, s0, s1, lane);
;     const float mx = mask_rowmax<MASK>(s0, s1, tp);
;     const bool was = rs.seen; rs.seen = was || (mx > -1e29f);
;     const bool trig = (mx > 8.f) || (!was && mx > -1e29f && mx < -8.f);
;     if (__builtin_expect(__any(trig), 0)) {
.LBB0_498:
	s_and_b64 vcc, exec, s[2:3]
	s_cbranch_vccz .LBB0_503
	s_nop 8
	ds_read_b128 v[50:53], v162 offset:36992
	ds_read_b128 v[34:37], v162 offset:36864
	ds_read_b128 v[38:41], v162 offset:36880
	ds_read_b128 v[54:57], v162 offset:37008
	ds_read_b128 v[42:45], v162 offset:36928
	ds_read_b128 v[58:61], v162 offset:37056
	ds_read_b128 v[46:49], v162 offset:36944
	ds_read_b128 v[62:65], v162 offset:37072
	ds_read_b128 v[66:69], v161 offset:4608
	ds_read_b128 v[70:73], v161
	ds_read_b128 v[74:77], v161 offset:32
	ds_read_b128 v[78:81], v161 offset:4640
	ds_read_b128 v[82:85], v161 offset:64
	ds_read_b128 v[86:89], v161 offset:4672
	ds_read_b128 v[90:93], v161 offset:96
	ds_read_b128 v[94:97], v161 offset:4704
	s_waitcnt lgkmcnt(11)
	v_pk_fma_f32 v[44:45], v[44:45], s[80:81], v[156:157] op_sel_hi:[1,0,0]
	v_pk_fma_f32 v[40:41], v[40:41], s[80:81], v[156:157] op_sel_hi:[1,0,0]
	v_pk_fma_f32 v[36:37], v[36:37], s[80:81], v[156:157] op_sel_hi:[1,0,0]
	s_waitcnt lgkmcnt(9)
	v_pk_fma_f32 v[46:47], v[46:47], s[80:81], v[156:157] op_sel_hi:[1,0,0]
	v_pk_fma_f32 v[42:43], v[42:43], s[80:81], v[156:157] op_sel_hi:[1,0,0]
	v_pk_fma_f32 v[38:39], v[38:39], s[80:81], v[156:157] op_sel_hi:[1,0,0]
	v_pk_fma_f32 v[34:35], v[34:35], s[80:81], v[156:157] op_sel_hi:[1,0,0]
	v_pk_fma_f32 v[56:57], v[56:57], s[80:81], v[156:157] op_sel_hi:[1,0,0]
	v_pk_fma_f32 v[52:53], v[52:53], s[80:81], v[156:157] op_sel_hi:[1,0,0]
	v_pk_fma_f32 v[54:55], v[54:55], s[80:81], v[156:157] op_sel_hi:[1,0,0]
	v_pk_fma_f32 v[50:51], v[50:51], s[80:81], v[156:157] op_sel_hi:[1,0,0]
	v_pk_fma_f32 v[48:49], v[48:49], s[80:81], v[156:157] op_sel_hi:[1,0,0]
	s_waitcnt lgkmcnt(8)
	v_pk_fma_f32 v[64:65], v[64:65], s[80:81], v[156:157] op_sel_hi:[1,0,0]
	v_pk_fma_f32 v[60:61], v[60:61], s[80:81], v[156:157] op_sel_hi:[1,0,0]
	v_pk_fma_f32 v[62:63], v[62:63], s[80:81], v[156:157] op_sel_hi:[1,0,0]
	v_pk_fma_f32 v[58:59], v[58:59], s[80:81], v[156:157] op_sel_hi:[1,0,0]
	s_setprio 1
	s_waitcnt lgkmcnt(6)
	v_mfma_f32_32x32x16_bf16 v[34:49], v[70:73], v[98:101], v[34:49]
	v_mfma_f32_32x32x16_bf16 v[50:65], v[66:69], v[98:101], v[50:65]
	s_waitcnt lgkmcnt(5)
	v_mfma_f32_32x32x16_bf16 v[34:49], v[74:77], v[102:105], v[34:49]
	s_waitcnt lgkmcnt(4)
	v_mfma_f32_32x32x16_bf16 v[50:65], v[78:81], v[102:105], v[50:65]
	s_waitcnt lgkmcnt(3)
	v_mfma_f32_32x32x16_bf16 v[34:49], v[82:85], v[106:109], v[34:49]
	s_waitcnt lgkmcnt(2)
	v_mfma_f32_32x32x16_bf16 v[50:65], v[86:89], v[106:109], v[50:65]
	s_waitcnt lgkmcnt(1)
	v_mfma_f32_32x32x16_bf16 v[34:49], v[90:93], v[110:113], v[34:49]
	s_waitcnt lgkmcnt(0)
	v_mfma_f32_32x32x16_bf16 v[50:65], v[94:97], v[110:113], v[50:65]
	s_setprio 0
	v_cmp_lt_i32_e32 vcc, 0, v158
	s_mov_b32 s2, 0xefa18f08
	s_nop 6
	v_cndmask_b32_e32 v72, v210, v35, vcc
	v_cmp_lt_i32_e32 vcc, -1, v158
	s_nop 1
	v_cndmask_b32_e32 v76, v210, v34, vcc
	v_cmp_lt_i32_e32 vcc, 32, v158
	s_nop 1
	v_cndmask_b32_e32 v66, v210, v51, vcc
	v_cmp_lt_i32_e32 vcc, 31, v158
	s_nop 1
	v_cndmask_b32_e32 v68, v210, v50, vcc
	v_cmp_lt_i32_e32 vcc, 2, v158
	s_nop 1
	v_cndmask_b32_e32 v71, v210, v37, vcc
	v_cmp_lt_i32_e32 vcc, 1, v158
	s_nop 1
	v_cndmask_b32_e32 v75, v210, v36, vcc
	v_cmp_lt_i32_e32 vcc, 34, v158
	s_nop 1
	v_cndmask_b32_e32 v53, v210, v53, vcc
	v_cmp_lt_i32_e32 vcc, 33, v158
	s_nop 1
	v_cndmask_b32_e32 v67, v210, v52, vcc
	v_cmp_lt_i32_e32 vcc, 4, v158
	s_nop 1
	v_cndmask_b32_e32 v70, v210, v39, vcc
	v_cmp_lt_i32_e32 vcc, 3, v158
	s_nop 1
	v_cndmask_b32_e32 v74, v210, v38, vcc
	v_cmp_lt_i32_e32 vcc, 36, v158
	s_nop 1
	v_cndmask_b32_e32 v51, v210, v55, vcc
	v_cmp_lt_i32_e32 vcc, 35, v158
	s_nop 1
	v_cndmask_b32_e32 v54, v210, v54, vcc
	v_cmp_lt_i32_e32 vcc, 6, v158
	s_nop 1
	v_cndmask_b32_e32 v69, v210, v41, vcc
	v_cmp_lt_i32_e32 vcc, 5, v158
	s_nop 1
	v_cndmask_b32_e32 v73, v210, v40, vcc
	v_cmp_lt_i32_e32 vcc, 38, v158
	s_nop 1
	v_cndmask_b32_e32 v50, v210, v57, vcc
	v_cmp_lt_i32_e32 vcc, 37, v158
	s_nop 1
	v_cndmask_b32_e32 v52, v210, v56, vcc
	v_cmp_lt_i32_e32 vcc, 16, v158
	s_nop 1
	v_cndmask_b32_e32 v55, v210, v43, vcc
	v_cmp_lt_i32_e32 vcc, 15, v158
	s_nop 1
	v_cndmask_b32_e32 v57, v210, v42, vcc
	v_cmp_lt_i32_e32 vcc, 48, v158
	s_nop 1
	v_cndmask_b32_e32 v38, v210, v59, vcc
	v_cmp_lt_i32_e32 vcc, 47, v158
	s_nop 1
	v_cndmask_b32_e32 v41, v210, v58, vcc
	v_cmp_lt_i32_e32 vcc, 18, v158
	s_nop 1
	v_cndmask_b32_e32 v45, v210, v45, vcc
	v_cmp_lt_i32_e32 vcc, 17, v158
	s_nop 1
	v_cndmask_b32_e32 v56, v210, v44, vcc
	v_cmp_lt_i32_e32 vcc, 50, v158
	s_nop 1
	v_cndmask_b32_e32 v36, v210, v61, vcc
	v_cmp_lt_i32_e32 vcc, 49, v158
	s_nop 1
	v_cndmask_b32_e32 v40, v210, v60, vcc
	v_cmp_lt_i32_e32 vcc, 20, v158
	s_nop 1
	v_cndmask_b32_e32 v43, v210, v47, vcc
	v_cmp_lt_i32_e32 vcc, 19, v158
	s_nop 1
	v_cndmask_b32_e32 v46, v210, v46, vcc
	v_cmp_lt_i32_e32 vcc, 52, v158
	s_nop 1
	v_cndmask_b32_e32 v35, v210, v63, vcc
	v_cmp_lt_i32_e32 vcc, 51, v158
	s_nop 1
	v_cndmask_b32_e32 v39, v210, v62, vcc
	v_cmp_lt_i32_e32 vcc, 22, v158
	s_nop 1
	v_cndmask_b32_e32 v42, v210, v49, vcc
	v_cmp_lt_i32_e32 vcc, 21, v158
	v_and_b32_e32 v49, 64, v209
	v_add_u32_e32 v49, 64, v49
	v_cndmask_b32_e32 v44, v210, v48, vcc
	v_cmp_lt_i32_e32 vcc, 54, v158
	v_max_f32_e32 v48, v42, v42
	s_nop 0
	v_cndmask_b32_e32 v34, v210, v65, vcc
	v_max_f32_e32 v47, v34, v34
	v_min_f32_e32 v47, v48, v47
	v_max3_f32 v48, v47, v76, v68
	v_max3_f32 v47, v47, v72, v66
	v_cmp_lt_i32_e32 vcc, 53, v158
	v_max3_f32 v48, v48, v75, v67
	v_max3_f32 v47, v47, v71, v53
	s_nop 0
	v_max3_f32 v48, v48, v74, v54
	v_max3_f32 v47, v47, v70, v51
	s_nop 0
	v_cndmask_b32_e32 v37, v210, v64, vcc
	v_max3_f32 v48, v48, v73, v52
	v_max3_f32 v47, v47, v69, v50
	s_nop 0
	v_max3_f32 v48, v48, v57, v41
	v_max3_f32 v47, v47, v55, v38
	s_nop 0
	v_max3_f32 v48, v48, v56, v40
	v_max3_f32 v47, v47, v45, v36
	s_nop 0
	v_max3_f32 v48, v48, v46, v39
	v_max3_f32 v47, v47, v43, v35
	s_nop 0
	v_max3_f32 v48, v48, v44, v37
	v_max3_f32 v47, v47, v42, v34
	s_nop 0
	v_max_f32_e32 v47, v47, v47
	v_max_f32_e32 v48, v48, v48
	v_max_f32_e32 v47, v48, v47
	v_xor_b32_e32 v48, 32, v209
	v_cmp_lt_i32_e32 vcc, v48, v49
	s_nop 1
	v_cndmask_b32_e32 v48, v209, v48, vcc
	v_lshlrev_b32_e32 v48, 2, v48
	ds_bpermute_b32 v48, v48, v47
	s_waitcnt lgkmcnt(0)
	v_max_f32_e32 v48, v48, v48
	v_max_f32_e32 v47, v47, v48
	v_cmp_lt_f32_e64 s[26:27], s2, v47
	s_mov_b32 s2, 0x41000000
	v_cmp_lt_f32_e32 vcc, s2, v47
	s_mov_b32 s2, 0xc1000000
	v_cmp_gt_f32_e64 s[2:3], s2, v47
	s_and_b64 s[2:3], s[2:3], s[26:27]
	s_andn2_b64 s[2:3], s[2:3], s[22:23]
	s_or_b64 s[2:3], s[2:3], vcc
	s_and_b64 vcc, exec, s[2:3]
	s_cbranch_vccnz .LBB0_515

; template <int MODE>
; DI void bias_init(f32x16& s0, f32x16& s1, const TP& tp, float fbm, int hi) {
; #pragma unroll
;     for (int r = 0; r < 16; ++r) {
;         const int kvc = 16 * (r >> 3) + (r & 7);
;         if (MODE == 0) { s0[r] = __builtin_fmaf(-L2E, tp.cs[kvc + 8 * hi], fbm); s1[r] = __builtin_fmaf(-L2E, tp.cs[kvc + 32 + 8 * hi], fbm); }
;         else { s0[r] = __builtin_fmaf(tp.sl, (float)kvc, fbm); s1[r] = __builtin_fmaf(tp.sl, (float)(kvc + 32), fbm); }
;     }
; }
; DI float max3_asm(float a, float b, float c) { float r; asm("v_max3_f32 %0, %1, %2, %3" : "=v"(r) : "v"(a), "v"(b), "v"(c)); return r; }
; template <bool MASK>
; DI float mask_rowmax(f32x16& s0, f32x16& s1, const TP& tp) {
;     if (MASK) {
; #pragma unroll
;         for (int r = 0; r < 16; ++r) {
;             const int kvc = 16 * (r >> 3) + (r & 7);
;             const bool v0 = tp.sel && (kvc <= tp.lim) && (kvc > tp.lim2), v1 = tp.sel && (kvc + 32 <= tp.lim) && (kvc + 32 > tp.lim2);
;             s0[r] = v0 ? s0[r] : -1e30f; s1[r] = v1 ? s1[r] : -1e30f;
;         }
;     }
;     const float seed = __builtin_fminf(s0[15], s1[15]);
;     float ma = seed, mb = seed;
; #pragma unroll
;     for (int r = 0; r < 16; r += 2) { ma = max3_asm(ma, s0[r], s1[r]); mb = max3_asm(mb, s0[r + 1], s1[r + 1]); }
;     const float mx = fmaxf(ma, mb);
;     return fmaxf(mx, __shfl_xor(mx, 32));
; }
; template <int MODE, bool MASK, bool WITH_O>
; DI void attn_tile_t(lptr Kt, lptr Vt, const bf16x8 (&qf)[4], f32x16& o0, f32x16& o1, RowState& rs, const TP& tp, int lane) {
;     const int hi = lane >> 5;
;     f32x16 s0, s1;
;     bias_init<MODE>(s0, s1, tp, tp.fb - rs.mref, hi);
;     qk_acc(Kt, qf, s0, s1, lane);
;     const float mx = mask_rowmax<MASK>(s0, s1, tp);
;     const bool was = rs.seen; rs.seen = was || (mx > -1e29f);
;     const bool trig = (mx > 8.f) || (!was && mx > -1e29f && mx < -8.f);
;     if (__builtin_expect(__any(trig), 0)) {
; DI void cmpwin_unit(const Params& P, lptr L, int u, int tid, int lane, int wid) {
;     ...
;         ATT_LOOP_BEGIN(NTC, false, kb_ + (size_t)(jt * 64) * 64, vb_ + (size_t)jt * 64, (const float*)nullptr)
;             const int n0 = jt * 64;
;             TP tp; tp.cs = nullptr; tp.sl = 16.f * sl; tp.fb = sl * (float)(16 * (n0 + 8 * hi) + 31 - t); tp.lim = nlim - n0 - 8 * hi; tp.lim2 = -(1 << 30); tp.sel = true;
.LBB0_526:
	v_cvt_f32_i32_e32 v2, v47
	s_and_b32 s43, s30, 1
	s_mul_i32 s2, s43, 0x2400
	s_add_i32 s52, s2, 0
	v_mul_f32_e32 v50, v150, v2
	s_cmp_gt_i32 s42, s29
	s_mov_b64 s[2:3], -1
	s_cbranch_scc1 .LBB0_535
	s_mov_b32 s2, 2.0
	v_sub_f32_e32 v2, v50, v49
	s_mov_b32 s3, 0x40400000
	v_add3_u32 v51, s52, v131, v133
	v_pk_fma_f32 v[20:21], v[80:81], s[2:3], v[2:3] op_sel_hi:[1,1,0]
	s_mov_b32 s2, 4.0
	ds_read_b128 v[52:55], v51 offset:4608
	ds_read_b128 v[56:59], v51
	ds_read_b128 v[60:63], v51 offset:32
	ds_read_b128 v[64:67], v51 offset:4640
	ds_read_b128 v[68:71], v51 offset:64
	ds_read_b128 v[88:91], v51 offset:4672
	ds_read_b128 v[92:95], v51 offset:96
	ds_read_b128 v[114:117], v51 offset:4704
	s_mov_b32 s3, 0x40a00000
	v_pk_fma_f32 v[22:23], v[80:81], s[2:3], v[2:3] op_sel_hi:[1,1,0]
	s_mov_b32 s2, 0x40c00000
	s_mov_b32 s3, 0x40e00000
	v_pk_fma_f32 v[24:25], v[80:81], s[2:3], v[2:3] op_sel_hi:[1,1,0]
	s_mov_b32 s2, 0x41800000
	s_mov_b32 s3, 0x41880000
	v_pk_fma_f32 v[26:27], v[80:81], s[2:3], v[2:3] op_sel_hi:[1,1,0]
	s_mov_b32 s2, 0x41900000
	s_mov_b32 s3, 0x41980000
	v_pk_fma_f32 v[28:29], v[80:81], s[2:3], v[2:3] op_sel_hi:[1,1,0]
	s_mov_b32 s2, 0x41a00000
	s_mov_b32 s3, 0x41a80000
	v_mov_b32_e32 v79, v78
	v_fma_f32 v18, 0, v78, v2
	v_add_f32_e32 v19, v78, v2
	v_pk_fma_f32 v[30:31], v[80:81], s[2:3], v[2:3] op_sel_hi:[1,1,0]
	v_pk_fma_f32 v[32:33], v[80:81], s[18:19], v[2:3] op_sel_hi:[1,1,0]
	v_pk_fma_f32 v[16:17], v[78:79], s[4:5], v[2:3] op_sel_hi:[1,1,0]
	v_pk_fma_f32 v[14:15], v[78:79], s[14:15], v[2:3] op_sel_hi:[1,1,0]
	v_pk_fma_f32 v[12:13], v[78:79], s[16:17], v[2:3] op_sel_hi:[1,1,0]
	v_pk_fma_f32 v[10:11], v[78:79], s[94:95], v[2:3] op_sel_hi:[1,1,0]
	v_pk_fma_f32 v[8:9], v[78:79], s[96:97], v[2:3] op_sel_hi:[1,1,0]
	v_pk_fma_f32 v[6:7], v[78:79], s[84:85], v[2:3] op_sel_hi:[1,1,0]
	v_pk_fma_f32 v[4:5], v[78:79], s[72:73], v[2:3] op_sel_hi:[1,1,0]
	v_pk_fma_f32 v[2:3], v[82:83], s[44:45], v[2:3] op_sel_hi:[1,1,0]
	s_setprio 1
	s_waitcnt vmcnt(4) lgkmcnt(6)
	v_mfma_f32_32x32x16_bf16 v[18:33], v[56:59], v[98:101], v[18:33]
	v_mfma_f32_32x32x16_bf16 v[2:17], v[52:55], v[98:101], v[2:17]
	s_waitcnt vmcnt(3) lgkmcnt(5)
	v_mfma_f32_32x32x16_bf16 v[18:33], v[60:63], v[102:105], v[18:33]
	s_waitcnt lgkmcnt(4)
	v_mfma_f32_32x32x16_bf16 v[2:17], v[64:67], v[102:105], v[2:17]
	s_waitcnt vmcnt(2) lgkmcnt(3)
	v_mfma_f32_32x32x16_bf16 v[18:33], v[68:71], v[106:109], v[18:33]
	s_waitcnt lgkmcnt(2)
	v_mfma_f32_32x32x16_bf16 v[2:17], v[88:91], v[106:109], v[2:17]
	s_waitcnt vmcnt(1) lgkmcnt(1)
	v_mfma_f32_32x32x16_bf16 v[18:33], v[92:95], v[110:113], v[18:33]
	s_waitcnt lgkmcnt(0)
	v_mfma_f32_32x32x16_bf16 v[2:17], v[114:117], v[110:113], v[2:17]
	s_setprio 0
	s_nop 10
	v_max_f32_e32 v51, v17, v17
	v_max_f32_e32 v52, v33, v33
	v_min_f32_e32 v51, v52, v51
	v_max3_f32 v52, v51, v18, v2
	v_max3_f32 v51, v51, v19, v3
	v_and_b32_e32 v53, 64, v209
	v_max3_f32 v52, v52, v20, v4
	v_max3_f32 v51, v51, v21, v5
	v_add_u32_e32 v53, 64, v53
	v_max3_f32 v52, v52, v22, v6
	v_max3_f32 v51, v51, v23, v7
	s_mov_b32 s2, 0xefa18f08
	v_max3_f32 v52, v52, v24, v8
	v_max3_f32 v51, v51, v25, v9
	s_mov_b64 s[26:27], -1
	v_max3_f32 v52, v52, v26, v10
	v_max3_f32 v51, v51, v27, v11
	s_nop 0
	v_max3_f32 v52, v52, v28, v12
	v_max3_f32 v51, v51, v29, v13
	s_nop 0
	v_max3_f32 v52, v52, v30, v14
	v_max3_f32 v51, v51, v31, v15
	s_nop 0
	v_max3_f32 v52, v52, v32, v16
	v_max3_f32 v51, v51, v33, v17
	s_nop 0
	v_max_f32_e32 v51, v51, v51
	v_max_f32_e32 v52, v52, v52
	v_max_f32_e32 v51, v52, v51
	v_xor_b32_e32 v52, 32, v209
	v_cmp_lt_i32_e32 vcc, v52, v53
	s_nop 1
	v_cndmask_b32_e32 v52, v209, v52, vcc
	v_lshlrev_b32_e32 v52, 2, v52
	ds_bpermute_b32 v52, v52, v51
	s_waitcnt lgkmcnt(0)
	v_max_f32_e32 v52, v52, v52
	v_max_f32_e32 v53, v51, v52
	v_cmp_lt_f32_e64 s[24:25], s2, v53
	s_mov_b32 s2, 0x41000000
	v_cmp_lt_f32_e32 vcc, s2, v53
	s_mov_b32 s26, 0xc1000000
	v_cmp_gt_f32_e64 s[26:27], s26, v53
	s_and_b64 s[26:27], s[26:27], s[24:25]
	s_andn2_b64 s[26:27], s[26:27], s[0:1]
	s_or_b64 s[26:27], s[26:27], vcc
	s_and_b64 vcc, exec, s[26:27]
	v_mov_b32_e32 v51, v49
	v_mov_b32_e32 v52, v46
	s_cbranch_vccnz .LBB0_540

; template <int MODE>
; DI void bias_init(f32x16& s0, f32x16& s1, const TP& tp, float fbm, int hi) {
; #pragma unroll
;     for (int r = 0; r < 16; ++r) {
;         const int kvc = 16 * (r >> 3) + (r & 7);
;         if (MODE == 0) { s0[r] = __builtin_fmaf(-L2E, tp.cs[kvc + 8 * hi], fbm); s1[r] = __builtin_fmaf(-L2E, tp.cs[kvc + 32 + 8 * hi], fbm); }
;         else { s0[r] = __builtin_fmaf(tp.sl, (float)kvc, fbm); s1[r] = __builtin_fmaf(tp.sl, (float)(kvc + 32), fbm); }
;     }
; }
; DI float max3_asm(float a, float b, float c) { float r; asm("v_max3_f32 %0, %1, %2, %3" : "=v"(r) : "v"(a), "v"(b), "v"(c)); return r; }
; template <bool MASK>
; DI float mask_rowmax(f32x16& s0, f32x16& s1, const TP& tp) {
;     if (MASK) {
; #pragma unroll
;         for (int r = 0; r < 16; ++r) {
;             const int kvc = 16 * (r >> 3) + (r & 7);
;             const bool v0 = tp.sel && (kvc <= tp.lim) && (kvc > tp.lim2), v1 = tp.sel && (kvc + 32 <= tp.lim) && (kvc + 32 > tp.lim2);
;             s0[r] = v0 ? s0[r] : -1e30f; s1[r] = v1 ? s1[r] : -1e30f;
;         }
;     }
;     const float seed = __builtin_fminf(s0[15], s1[15]);
;     float ma = seed, mb = seed;
; #pragma unroll
;     for (int r = 0; r < 16; r += 2) { ma = max3_asm(ma, s0[r], s1[r]); mb = max3_asm(mb, s0[r + 1], s1[r + 1]); }
;     const float mx = fmaxf(ma, mb);
;     return fmaxf(mx, __shfl_xor(mx, 32));
; }
; template <int MODE, bool MASK, bool WITH_O>
; DI void attn_tile_t(lptr Kt, lptr Vt, const bf16x8 (&qf)[4], f32x16& o0, f32x16& o1, RowState& rs, const TP& tp, int lane) {
;     const int hi = lane >> 5;
;     f32x16 s0, s1;
;     bias_init<MODE>(s0, s1, tp, tp.fb - rs.mref, hi);
;     qk_acc(Kt, qf, s0, s1, lane);
;     const float mx = mask_rowmax<MASK>(s0, s1, tp);
;     const bool was = rs.seen; rs.seen = was || (mx > -1e29f);
;     const bool trig = (mx > 8.f) || (!was && mx > -1e29f && mx < -8.f);
;     if (__builtin_expect(__any(trig), 0)) {
; DI void cmpwin_unit(const Params& P, lptr L, int u, int tid, int lane, int wid) {
;     ...
;         ATT_LOOP_BEGIN(NTC, false, kb_ + (size_t)(jt * 64) * 64, vb_ + (size_t)jt * 64, (const float*)nullptr)
;             const int n0 = jt * 64;
;             TP tp; tp.cs = nullptr; tp.sl = 16.f * sl; tp.fb = sl * (float)(16 * (n0 + 8 * hi) + 31 - t); tp.lim = nlim - n0 - 8 * hi; tp.lim2 = -(1 << 30); tp.sel = true;
.LBB0_535:
	s_and_b64 vcc, exec, s[2:3]
	s_cbranch_vccz .LBB0_531
	v_sub_f32_e32 v18, v50, v49
	s_mov_b32 s2, 2.0
	v_mov_b32_e32 v79, v78
	s_mov_b32 s3, 0x40400000
	v_pk_fma_f32 v[32:33], v[78:79], s[4:5], v[18:19] op_sel_hi:[1,1,0]
	v_pk_fma_f32 v[30:31], v[78:79], s[14:15], v[18:19] op_sel_hi:[1,1,0]
	v_pk_fma_f32 v[28:29], v[78:79], s[16:17], v[18:19] op_sel_hi:[1,1,0]
	v_pk_fma_f32 v[26:27], v[78:79], s[94:95], v[18:19] op_sel_hi:[1,1,0]
	v_pk_fma_f32 v[24:25], v[78:79], s[96:97], v[18:19] op_sel_hi:[1,1,0]
	v_pk_fma_f32 v[22:23], v[78:79], s[84:85], v[18:19] op_sel_hi:[1,1,0]
	v_pk_fma_f32 v[20:21], v[78:79], s[72:73], v[18:19] op_sel_hi:[1,1,0]
	v_add3_u32 v79, s52, v131, v133
	v_pk_fma_f32 v[4:5], v[80:81], s[2:3], v[18:19] op_sel_hi:[1,1,0]
	s_mov_b32 s2, 4.0
	ds_read_b128 v[50:53], v79 offset:4608
	ds_read_b128 v[54:57], v79
	ds_read_b128 v[58:61], v79 offset:32
	ds_read_b128 v[62:65], v79 offset:4640
	ds_read_b128 v[66:69], v79 offset:64
	ds_read_b128 v[70:73], v79 offset:4672
	ds_read_b128 v[88:91], v79 offset:96
	ds_read_b128 v[92:95], v79 offset:4704
	s_mov_b32 s3, 0x40a00000
	v_pk_fma_f32 v[6:7], v[80:81], s[2:3], v[18:19] op_sel_hi:[1,1,0]
	s_mov_b32 s2, 0x40c00000
	s_mov_b32 s3, 0x40e00000
	v_pk_fma_f32 v[8:9], v[80:81], s[2:3], v[18:19] op_sel_hi:[1,1,0]
	s_mov_b32 s2, 0x41800000
	s_mov_b32 s3, 0x41880000
	v_pk_fma_f32 v[10:11], v[80:81], s[2:3], v[18:19] op_sel_hi:[1,1,0]
	s_mov_b32 s2, 0x41900000
	s_mov_b32 s3, 0x41980000
	v_pk_fma_f32 v[12:13], v[80:81], s[2:3], v[18:19] op_sel_hi:[1,1,0]
	s_mov_b32 s2, 0x41a00000
	s_mov_b32 s3, 0x41a80000
	v_fma_f32 v2, 0, v78, v18
	v_add_f32_e32 v3, v78, v18
	v_pk_fma_f32 v[14:15], v[80:81], s[2:3], v[18:19] op_sel_hi:[1,1,0]
	v_pk_fma_f32 v[16:17], v[80:81], s[18:19], v[18:19] op_sel_hi:[1,1,0]
	v_pk_fma_f32 v[18:19], v[82:83], s[44:45], v[18:19] op_sel_hi:[1,1,0]
	s_setprio 1
	s_waitcnt vmcnt(4) lgkmcnt(6)
	v_mfma_f32_32x32x16_bf16 v[2:17], v[54:57], v[98:101], v[2:17]
	v_mfma_f32_32x32x16_bf16 v[18:33], v[50:53], v[98:101], v[18:33]
	s_waitcnt vmcnt(3) lgkmcnt(5)
	v_mfma_f32_32x32x16_bf16 v[2:17], v[58:61], v[102:105], v[2:17]
	s_waitcnt lgkmcnt(4)
	v_mfma_f32_32x32x16_bf16 v[18:33], v[62:65], v[102:105], v[18:33]
	s_waitcnt vmcnt(2) lgkmcnt(3)
	v_mfma_f32_32x32x16_bf16 v[2:17], v[66:69], v[106:109], v[2:17]
	s_waitcnt lgkmcnt(2)
	v_mfma_f32_32x32x16_bf16 v[18:33], v[70:73], v[106:109], v[18:33]
	s_waitcnt vmcnt(1) lgkmcnt(1)
	v_mfma_f32_32x32x16_bf16 v[2:17], v[88:91], v[110:113], v[2:17]
	s_waitcnt lgkmcnt(0)
	v_mfma_f32_32x32x16_bf16 v[18:33], v[92:95], v[110:113], v[18:33]
	s_setprio 0
	v_cmp_lt_i32_e32 vcc, 0, v48
	s_mov_b32 s2, 0xefa18f08
	s_nop 6
	v_cndmask_b32_e32 v51, v210, v3, vcc
	v_cmp_lt_i32_e32 vcc, -1, v48
	s_nop 1
	v_cndmask_b32_e32 v55, v210, v2, vcc
	v_cmp_lt_i32_e32 vcc, 32, v48
	s_nop 1
	v_cndmask_b32_e32 v53, v210, v19, vcc
	v_cmp_lt_i32_e32 vcc, 31, v48
	s_nop 1
	v_cndmask_b32_e32 v58, v210, v18, vcc
	v_cmp_lt_i32_e32 vcc, 2, v48
	s_nop 1
	v_cndmask_b32_e32 v50, v210, v5, vcc
	v_cmp_lt_i32_e32 vcc, 1, v48
	s_nop 1
	v_cndmask_b32_e32 v57, v210, v4, vcc
	v_cmp_lt_i32_e32 vcc, 34, v48
	s_nop 1
	v_cndmask_b32_e32 v21, v210, v21, vcc
	v_cmp_lt_i32_e32 vcc, 33, v48
	s_nop 1
	v_cndmask_b32_e32 v59, v210, v20, vcc
	v_cmp_lt_i32_e32 vcc, 4, v48
	s_nop 1
	v_cndmask_b32_e32 v18, v210, v7, vcc
	v_cmp_lt_i32_e32 vcc, 3, v48
	s_nop 1
	v_cndmask_b32_e32 v54, v210, v6, vcc
	v_cmp_lt_i32_e32 vcc, 36, v48
	s_nop 1
	v_cndmask_b32_e32 v20, v210, v23, vcc
	v_cmp_lt_i32_e32 vcc, 35, v48
	s_nop 1
	v_cndmask_b32_e32 v56, v210, v22, vcc
	v_cmp_lt_i32_e32 vcc, 6, v48
	s_nop 1
	v_cndmask_b32_e32 v9, v210, v9, vcc
	v_cmp_lt_i32_e32 vcc, 5, v48
	s_nop 1
	v_cndmask_b32_e32 v52, v210, v8, vcc
	v_cmp_lt_i32_e32 vcc, 38, v48
	s_nop 1
	v_cndmask_b32_e32 v19, v210, v25, vcc
	v_cmp_lt_i32_e32 vcc, 37, v48
	s_nop 1
	v_cndmask_b32_e32 v25, v210, v24, vcc
	v_cmp_lt_i32_e32 vcc, 16, v48
	s_nop 1
	v_cndmask_b32_e32 v6, v210, v11, vcc
	v_cmp_lt_i32_e32 vcc, 15, v48
	s_nop 1
	v_cndmask_b32_e32 v22, v210, v10, vcc
	v_cmp_lt_i32_e32 vcc, 48, v48
	s_nop 1
	v_cndmask_b32_e32 v8, v210, v27, vcc
	v_cmp_lt_i32_e32 vcc, 47, v48
	s_nop 1
	v_cndmask_b32_e32 v24, v210, v26, vcc
	v_cmp_lt_i32_e32 vcc, 18, v48
	v_and_b32_e32 v26, 64, v209
	v_add_u32_e32 v26, 64, v26
	v_cndmask_b32_e32 v4, v210, v13, vcc
	v_cmp_lt_i32_e32 vcc, 17, v48
	s_nop 1
	v_cndmask_b32_e32 v13, v210, v12, vcc
	v_cmp_lt_i32_e32 vcc, 50, v48
	s_nop 1
	v_cndmask_b32_e32 v7, v210, v29, vcc
	v_cmp_lt_i32_e32 vcc, 49, v48
	s_nop 1
	v_cndmask_b32_e32 v23, v210, v28, vcc
	v_cmp_lt_i32_e32 vcc, 20, v48
	s_nop 1
	v_cndmask_b32_e32 v3, v210, v15, vcc
	v_cmp_lt_i32_e32 vcc, 19, v48
	s_nop 1
	v_cndmask_b32_e32 v11, v210, v14, vcc
	v_cmp_lt_i32_e32 vcc, 52, v48
	s_nop 1
	v_cndmask_b32_e32 v5, v210, v31, vcc
	v_cmp_lt_i32_e32 vcc, 51, v48
	s_nop 1
	v_cndmask_b32_e32 v14, v210, v30, vcc
	v_cmp_lt_i32_e32 vcc, 22, v48
	s_nop 1
	v_cndmask_b32_e32 v2, v210, v17, vcc
	v_cmp_lt_i32_e32 vcc, 21, v48
	s_nop 1
	v_cndmask_b32_e32 v10, v210, v16, vcc
	v_cmp_lt_i32_e32 vcc, 54, v48
	v_max_f32_e32 v16, v2, v2
	s_nop 0
	v_cndmask_b32_e32 v17, v210, v33, vcc
	v_max_f32_e32 v15, v17, v17
	v_min_f32_e32 v15, v16, v15
	v_max3_f32 v16, v15, v55, v58
	v_max3_f32 v15, v15, v51, v53
	v_cmp_lt_i32_e32 vcc, 53, v48
	v_max3_f32 v16, v16, v57, v59
	v_max3_f32 v15, v15, v50, v21
	s_nop 0
	v_max3_f32 v16, v16, v54, v56
	v_max3_f32 v15, v15, v18, v20
	s_nop 0
	v_cndmask_b32_e32 v12, v210, v32, vcc
	v_max3_f32 v16, v16, v52, v25
	v_max3_f32 v15, v15, v9, v19
	s_nop 0
	v_max3_f32 v16, v16, v22, v24
	v_max3_f32 v15, v15, v6, v8
	s_nop 0
	v_max3_f32 v16, v16, v13, v23
	v_max3_f32 v15, v15, v4, v7
	s_nop 0
	v_max3_f32 v16, v16, v11, v14
	v_max3_f32 v15, v15, v3, v5
	s_nop 0
	v_max3_f32 v16, v16, v10, v12
	v_max3_f32 v15, v15, v2, v17
	s_nop 0
	v_max_f32_e32 v15, v15, v15
	v_max_f32_e32 v16, v16, v16
	v_max_f32_e32 v15, v16, v15
	v_xor_b32_e32 v16, 32, v209
	v_cmp_lt_i32_e32 vcc, v16, v26
	s_nop 1
	v_cndmask_b32_e32 v16, v209, v16, vcc
	v_lshlrev_b32_e32 v16, 2, v16
	ds_bpermute_b32 v16, v16, v15
	s_waitcnt lgkmcnt(0)
	v_max_f32_e32 v16, v16, v16
	v_max_f32_e32 v15, v15, v16
	v_cmp_lt_f32_e64 s[24:25], s2, v15
	s_mov_b32 s2, 0x41000000
	v_cmp_lt_f32_e32 vcc, s2, v15
	s_mov_b32 s2, 0xc1000000
	v_cmp_gt_f32_e64 s[2:3], s2, v15
	s_and_b64 s[2:3], s[2:3], s[24:25]
	s_andn2_b64 s[2:3], s[2:3], s[0:1]
	s_or_b64 s[2:3], s[2:3], vcc
	s_and_b64 vcc, exec, s[2:3]
	s_cbranch_vccnz .LBB0_541

; template <int MODE>
; DI void bias_init(f32x16& s0, f32x16& s1, const TP& tp, float fbm, int hi) {
; #pragma unroll
;     for (int r = 0; r < 16; ++r) {
;         const int kvc = 16 * (r >> 3) + (r & 7);
;         if (MODE == 0) { s0[r] = __builtin_fmaf(-L2E, tp.cs[kvc + 8 * hi], fbm); s1[r] = __builtin_fmaf(-L2E, tp.cs[kvc + 32 + 8 * hi], fbm); }
;         else { s0[r] = __builtin_fmaf(tp.sl, (float)kvc, fbm); s1[r] = __builtin_fmaf(tp.sl, (float)(kvc + 32), fbm); }
;     }
; }
; DI float max3_asm(float a, float b, float c) { float r; asm("v_max3_f32 %0, %1, %2, %3" : "=v"(r) : "v"(a), "v"(b), "v"(c)); return r; }
; template <bool MASK>
; DI float mask_rowmax(f32x16& s0, f32x16& s1, const TP& tp) {
;     if (MASK) {
; #pragma unroll
;         for (int r = 0; r < 16; ++r) {
;             const int kvc = 16 * (r >> 3) + (r & 7);
;             const bool v0 = tp.sel && (kvc <= tp.lim) && (kvc > tp.lim2), v1 = tp.sel && (kvc + 32 <= tp.lim) && (kvc + 32 > tp.lim2);
;             s0[r] = v0 ? s0[r] : -1e30f; s1[r] = v1 ? s1[r] : -1e30f;
;         }
;     }
;     const float seed = __builtin_fminf(s0[15], s1[15]);
;     float ma = seed, mb = seed;
; #pragma unroll
;     for (int r = 0; r < 16; r += 2) { ma = max3_asm(ma, s0[r], s1[r]); mb = max3_asm(mb, s0[r + 1], s1[r + 1]); }
;     const float mx = fmaxf(ma, mb);
;     return fmaxf(mx, __shfl_xor(mx, 32));
; }
; template <int MODE, bool MASK, bool WITH_O>
; DI void attn_tile_t(lptr Kt, lptr Vt, const bf16x8 (&qf)[4], f32x16& o0, f32x16& o1, RowState& rs, const TP& tp, int lane) {
;     const int hi = lane >> 5;
;     f32x16 s0, s1;
;     bias_init<MODE>(s0, s1, tp, tp.fb - rs.mref, hi);
;     qk_acc(Kt, qf, s0, s1, lane);
;     const float mx = mask_rowmax<MASK>(s0, s1, tp);
;     const bool was = rs.seen; rs.seen = was || (mx > -1e29f);
;     const bool trig = (mx > 8.f) || (!was && mx > -1e29f && mx < -8.f);
;     if (__builtin_expect(__any(trig), 0)) {
; DI void cmpwin_unit(const Params& P, lptr L, int u, int tid, int lane, int wid) {
;     ...
;         ATT_LOOP_BEGIN(NTW, false, kb_ + (size_t)((jw0 + jt) * 64) * PROJ_LD, vb_ + (size_t)(jw0 + jt) * 64, (const float*)nullptr)
;             const int kv0 = (jw0 + jt) * 64;
;             TP tp; tp.cs = nullptr; tp.sl = sl; tp.fb = sl * (float)(kv0 + 8 * hi - t); tp.lim = t - kv0 - 8 * hi; tp.lim2 = tp.lim - 512; tp.sel = true;
.LBB0_581:
	s_and_b32 s54, s53, 1
	s_mul_i32 s2, s54, 0x2400
	v_add_u32_e32 v34, s43, v161
	s_add_i32 s55, s2, 0
	s_add_i32 s2, s43, 63
	v_cvt_f32_i32_e32 v34, v34
	s_cmp_gt_u32 s2, s81
	s_cselect_b64 s[2:3], -1, 0
	s_cmp_lt_i32 s43, s23
	s_cselect_b64 s[28:29], -1, 0
	s_or_b64 s[2:3], s[2:3], s[28:29]
	v_mul_f32_e32 v216, v150, v34
	s_andn2_b64 vcc, exec, s[2:3]
	s_mov_b64 s[2:3], -1
	s_cbranch_vccz .LBB0_590
	s_mov_b32 s2, 2.0
	v_sub_f32_e32 v34, v216, v215
	s_mov_b32 s3, 0x40400000
	v_pk_fma_f32 v[84:85], v[166:167], s[2:3], v[34:35] op_sel_hi:[1,1,0]
	s_mov_b32 s2, 4.0
	s_mov_b32 s3, 0x40a00000
	v_pk_fma_f32 v[86:87], v[166:167], s[2:3], v[34:35] op_sel_hi:[1,1,0]
	s_mov_b32 s2, 0x40c00000
	s_mov_b32 s3, 0x40e00000
	v_pk_fma_f32 v[88:89], v[166:167], s[2:3], v[34:35] op_sel_hi:[1,1,0]
	s_mov_b32 s2, 0x41800000
	s_mov_b32 s3, 0x41880000
	v_pk_fma_f32 v[90:91], v[166:167], s[2:3], v[34:35] op_sel_hi:[1,1,0]
	s_mov_b32 s2, 0x41900000
	s_mov_b32 s3, 0x41980000
	v_pk_fma_f32 v[92:93], v[166:167], s[2:3], v[34:35] op_sel_hi:[1,1,0]
	s_mov_b32 s2, 0x41a00000
	s_mov_b32 s3, 0x41a80000
	v_mov_b32_e32 v151, v150
	v_add3_u32 v62, s55, v131, v133
	v_fma_f32 v82, 0, v150, v34
	v_add_f32_e32 v83, v150, v34
	v_pk_fma_f32 v[94:95], v[166:167], s[2:3], v[34:35] op_sel_hi:[1,1,0]
	v_pk_fma_f32 v[96:97], v[166:167], s[18:19], v[34:35] op_sel_hi:[1,1,0]
	v_pk_fma_f32 v[80:81], v[150:151], s[4:5], v[34:35] op_sel_hi:[1,1,0]
	v_pk_fma_f32 v[78:79], v[150:151], s[14:15], v[34:35] op_sel_hi:[1,1,0]
	v_pk_fma_f32 v[76:77], v[150:151], s[16:17], v[34:35] op_sel_hi:[1,1,0]
	v_pk_fma_f32 v[74:75], v[150:151], s[94:95], v[34:35] op_sel_hi:[1,1,0]
	v_pk_fma_f32 v[72:73], v[150:151], s[96:97], v[34:35] op_sel_hi:[1,1,0]
	v_pk_fma_f32 v[70:71], v[150:151], s[84:85], v[34:35] op_sel_hi:[1,1,0]
	v_pk_fma_f32 v[68:69], v[150:151], s[72:73], v[34:35] op_sel_hi:[1,1,0]
	v_pk_fma_f32 v[66:67], v[168:169], s[44:45], v[34:35] op_sel_hi:[1,1,0]
	ds_read_b128 v[34:37], v62 offset:4608
	ds_read_b128 v[38:41], v62
	ds_read_b128 v[42:45], v62 offset:32
	ds_read_b128 v[46:49], v62 offset:4640
	ds_read_b128 v[50:53], v62 offset:64
	ds_read_b128 v[54:57], v62 offset:4672
	ds_read_b128 v[58:61], v62 offset:96
	ds_read_b128 v[62:65], v62 offset:4704
	s_setprio 1
	s_waitcnt lgkmcnt(6)
	v_mfma_f32_32x32x16_bf16 v[82:97], v[38:41], v[98:101], v[82:97]
	v_mfma_f32_32x32x16_bf16 v[66:81], v[34:37], v[98:101], v[66:81]
	s_waitcnt lgkmcnt(5)
	v_mfma_f32_32x32x16_bf16 v[82:97], v[42:45], v[102:105], v[82:97]
	s_waitcnt lgkmcnt(4)
	v_mfma_f32_32x32x16_bf16 v[66:81], v[46:49], v[102:105], v[66:81]
	s_waitcnt lgkmcnt(3)
	v_mfma_f32_32x32x16_bf16 v[82:97], v[50:53], v[106:109], v[82:97]
	s_waitcnt lgkmcnt(2)
	v_mfma_f32_32x32x16_bf16 v[66:81], v[54:57], v[106:109], v[66:81]
	s_waitcnt lgkmcnt(1)
	v_mfma_f32_32x32x16_bf16 v[82:97], v[58:61], v[110:113], v[82:97]
	s_waitcnt lgkmcnt(0)
	v_mfma_f32_32x32x16_bf16 v[66:81], v[62:65], v[110:113], v[66:81]
	s_setprio 0
	s_nop 10
	v_max_f32_e32 v34, v81, v81
	v_max_f32_e32 v35, v97, v97
	v_min_f32_e32 v34, v35, v34
	v_max3_f32 v35, v34, v82, v66
	v_max3_f32 v34, v34, v83, v67
	s_mov_b32 s2, 0xefa18f08
	v_max3_f32 v35, v35, v84, v68
	v_max3_f32 v34, v34, v85, v69
	s_mov_b64 s[30:31], -1
	v_max3_f32 v35, v35, v86, v70
	v_max3_f32 v34, v34, v87, v71
	s_nop 0
	v_max3_f32 v35, v35, v88, v72
	v_max3_f32 v34, v34, v89, v73
	s_nop 0
	v_max3_f32 v35, v35, v90, v74
	v_max3_f32 v34, v34, v91, v75
	s_nop 0
	v_max3_f32 v35, v35, v92, v76
	v_max3_f32 v34, v34, v93, v77
	s_nop 0
	v_max3_f32 v35, v35, v94, v78
	v_max3_f32 v34, v34, v95, v79
	s_nop 0
	v_max3_f32 v35, v35, v96, v80
	v_max3_f32 v34, v34, v97, v81
	s_nop 0
	v_max_f32_e32 v34, v34, v34
	v_max_f32_e32 v35, v35, v35
	v_max_f32_e32 v34, v35, v34
	ds_bpermute_b32 v35, v149, v34
	s_waitcnt lgkmcnt(0)
	v_max_f32_e32 v35, v35, v35
	v_max_f32_e32 v218, v34, v35
	v_cmp_lt_f32_e64 s[28:29], s2, v218
	s_mov_b32 s2, 0x41000000
	v_cmp_lt_f32_e32 vcc, s2, v218
	s_mov_b32 s30, 0xc1000000
	v_cmp_gt_f32_e64 s[30:31], s30, v218
	s_and_b64 s[30:31], s[30:31], s[28:29]
	s_andn2_b64 s[30:31], s[30:31], s[24:25]
	s_or_b64 s[30:31], s[30:31], vcc
	s_and_b64 vcc, exec, s[30:31]
	v_mov_b32_e32 v217, v163
	v_mov_b32_e32 v151, v215
	s_cbranch_vccnz .LBB0_595

; #define LAS __attribute__((address_space(3)))
; #define MFMA32(a, b, c) __builtin_amdgcn_mfma_f32_32x32x16_bf16((a), (b), (c), 0, 0, 0)
; DI void qk_acc(lptr Kt, const bf16x8 (&qf)[4], f32x16& s0, f32x16& s1, int lane) {
;     const int i = lane & 31, hi = lane >> 5;
;     const int krow = (i & 19) | ((i & 4) << 1) | ((i & 8) >> 1);
;     lptr kp = Kt + krow * KPB + hi * 16;
;     bf16x8 a0[4], a1[4];
; #pragma unroll
;     for (int d0 = 0; d0 < 4; ++d0) { a0[d0] = *(LAS bf16x8*)(kp + d0 * 32); a1[d0] = *(LAS bf16x8*)(kp + 32 * KPB + d0 * 32); }
;     __builtin_amdgcn_s_setprio(1);
; #pragma unroll
;     for (int d0 = 0; d0 < 4; ++d0) { s0 = MFMA32(a0[d0], qf[d0], s0); s1 = MFMA32(a1[d0], qf[d0], s1); }
;     __builtin_amdgcn_s_setprio(0);
; }
; template <int MODE>
; DI void bias_init(f32x16& s0, f32x16& s1, const TP& tp, float fbm, int hi) {
; #pragma unroll
;     for (int r = 0; r < 16; ++r) {
;         const int kvc = 16 * (r >> 3) + (r & 7);
;         if (MODE == 0) { s0[r] = __builtin_fmaf(-L2E, tp.cs[kvc + 8 * hi], fbm); s1[r] = __builtin_fmaf(-L2E, tp.cs[kvc + 32 + 8 * hi], fbm); }
;         else { s0[r] = __builtin_fmaf(tp.sl, (float)kvc, fbm); s1[r] = __builtin_fmaf(tp.sl, (float)(kvc + 32), fbm); }
.LBB0_590:
	s_and_b64 vcc, exec, s[2:3]
	s_cbranch_vccz .LBB0_586
	s_mov_b32 s2, 2.0
	v_sub_f32_e32 v50, v216, v215
	s_mov_b32 s3, 0x40400000
	v_add3_u32 v94, s55, v131, v133
	v_pk_fma_f32 v[36:37], v[166:167], s[2:3], v[50:51] op_sel_hi:[1,1,0]
	s_mov_b32 s2, 4.0
	ds_read_b128 v[66:69], v94 offset:4608
	ds_read_b128 v[70:73], v94
	ds_read_b128 v[74:77], v94 offset:32
	ds_read_b128 v[78:81], v94 offset:4640
	ds_read_b128 v[82:85], v94 offset:64
	ds_read_b128 v[86:89], v94 offset:4672
	ds_read_b128 v[90:93], v94 offset:96
	ds_read_b128 v[94:97], v94 offset:4704
	s_mov_b32 s3, 0x40a00000
	v_pk_fma_f32 v[38:39], v[166:167], s[2:3], v[50:51] op_sel_hi:[1,1,0]
	s_mov_b32 s2, 0x40c00000
	s_mov_b32 s3, 0x40e00000
	v_pk_fma_f32 v[40:41], v[166:167], s[2:3], v[50:51] op_sel_hi:[1,1,0]
	s_mov_b32 s2, 0x41800000
	s_mov_b32 s3, 0x41880000
	v_pk_fma_f32 v[42:43], v[166:167], s[2:3], v[50:51] op_sel_hi:[1,1,0]
	s_mov_b32 s2, 0x41900000
	s_mov_b32 s3, 0x41980000
	v_pk_fma_f32 v[44:45], v[166:167], s[2:3], v[50:51] op_sel_hi:[1,1,0]
	s_mov_b32 s2, 0x41a00000
	s_mov_b32 s3, 0x41a80000
	v_mov_b32_e32 v151, v150
	v_fma_f32 v34, 0, v150, v50
	v_add_f32_e32 v35, v150, v50
	v_pk_fma_f32 v[46:47], v[166:167], s[2:3], v[50:51] op_sel_hi:[1,1,0]
	v_pk_fma_f32 v[48:49], v[166:167], s[18:19], v[50:51] op_sel_hi:[1,1,0]
	v_pk_fma_f32 v[64:65], v[150:151], s[4:5], v[50:51] op_sel_hi:[1,1,0]
	v_pk_fma_f32 v[62:63], v[150:151], s[14:15], v[50:51] op_sel_hi:[1,1,0]
	v_pk_fma_f32 v[60:61], v[150:151], s[16:17], v[50:51] op_sel_hi:[1,1,0]
	v_pk_fma_f32 v[58:59], v[150:151], s[94:95], v[50:51] op_sel_hi:[1,1,0]
	v_pk_fma_f32 v[56:57], v[150:151], s[96:97], v[50:51] op_sel_hi:[1,1,0]
	v_pk_fma_f32 v[54:55], v[150:151], s[84:85], v[50:51] op_sel_hi:[1,1,0]
	v_pk_fma_f32 v[52:53], v[150:151], s[72:73], v[50:51] op_sel_hi:[1,1,0]
	v_pk_fma_f32 v[50:51], v[168:169], s[44:45], v[50:51] op_sel_hi:[1,1,0]
	s_setprio 1
	s_waitcnt lgkmcnt(6)
	v_mfma_f32_32x32x16_bf16 v[34:49], v[70:73], v[98:101], v[34:49]
	v_mfma_f32_32x32x16_bf16 v[50:65], v[66:69], v[98:101], v[50:65]
	s_waitcnt lgkmcnt(5)
	v_mfma_f32_32x32x16_bf16 v[34:49], v[74:77], v[102:105], v[34:49]
	s_waitcnt lgkmcnt(4)
	v_mfma_f32_32x32x16_bf16 v[50:65], v[78:81], v[102:105], v[50:65]
	s_waitcnt lgkmcnt(3)
	v_mfma_f32_32x32x16_bf16 v[34:49], v[82:85], v[106:109], v[34:49]
	s_waitcnt lgkmcnt(2)
	v_mfma_f32_32x32x16_bf16 v[50:65], v[86:89], v[106:109], v[50:65]
	s_waitcnt lgkmcnt(1)
	v_mfma_f32_32x32x16_bf16 v[34:49], v[90:93], v[110:113], v[34:49]
	s_waitcnt lgkmcnt(0)
; DI float max3_asm(float a, float b, float c) { float r; asm("v_max3_f32 %0, %1, %2, %3" : "=v"(r) : "v"(a), "v"(b), "v"(c)); return r; }
; template <bool MASK>
; DI float mask_rowmax(f32x16& s0, f32x16& s1, const TP& tp) {
;     if (MASK) {
; #pragma unroll
;         for (int r = 0; r < 16; ++r) {
;             const int kvc = 16 * (r >> 3) + (r & 7);
;             const bool v0 = tp.sel && (kvc <= tp.lim) && (kvc > tp.lim2), v1 = tp.sel && (kvc + 32 <= tp.lim) && (kvc + 32 > tp.lim2);
;             s0[r] = v0 ? s0[r] : -1e30f; s1[r] = v1 ? s1[r] : -1e30f;
;         }
;     }
;     const float seed = __builtin_fminf(s0[15], s1[15]);
;     float ma = seed, mb = seed;
; #pragma unroll
;     for (int r = 0; r < 16; r += 2) { ma = max3_asm(ma, s0[r], s1[r]); mb = max3_asm(mb, s0[r + 1], s1[r + 1]); }
;     const float mx = fmaxf(ma, mb);
;     return fmaxf(mx, __shfl_xor(mx, 32));
; }
; template <int MODE, bool MASK, bool WITH_O>
; DI void attn_tile_t(lptr Kt, lptr Vt, const bf16x8 (&qf)[4], f32x16& o0, f32x16& o1, RowState& rs, const TP& tp, int lane) {
;     const int hi = lane >> 5;
;     f32x16 s0, s1;
;     bias_init<MODE>(s0, s1, tp, tp.fb - rs.mref, hi);
;     qk_acc(Kt, qf, s0, s1, lane);
;     const float mx = mask_rowmax<MASK>(s0, s1, tp);
;     const bool was = rs.seen; rs.seen = was || (mx > -1e29f);
;     const bool trig = (mx > 8.f) || (!was && mx > -1e29f && mx < -8.f);
;     if (__builtin_expect(__any(trig), 0)) {
	v_mfma_f32_32x32x16_bf16 v[50:65], v[94:97], v[110:113], v[50:65]
	s_setprio 0
	v_add_u32_e32 v66, -1, v155
	v_cmp_gt_u32_e32 vcc, s10, v66
	s_mov_b32 s2, 0xefa18f08
	s_nop 5
	v_cndmask_b32_e32 v68, v210, v35, vcc
	v_cmp_gt_u32_e32 vcc, s10, v155
	v_subrev_u32_e32 v35, 32, v155
	s_nop 0
	v_cndmask_b32_e32 v75, v210, v34, vcc
	v_subrev_u32_e32 v34, 33, v155
	v_cmp_gt_u32_e32 vcc, s10, v34
	v_add_u32_e32 v34, -3, v155
	s_nop 0
	v_cndmask_b32_e32 v51, v210, v51, vcc
	v_cmp_gt_u32_e32 vcc, s10, v35
	v_add_u32_e32 v35, -2, v155
	s_nop 0
	v_cndmask_b32_e32 v67, v210, v50, vcc
	v_cmp_gt_u32_e32 vcc, s10, v34
	v_subrev_u32_e32 v34, 35, v155
	s_nop 0
	v_cndmask_b32_e32 v69, v210, v37, vcc
	v_cmp_gt_u32_e32 vcc, s10, v35
	v_subrev_u32_e32 v35, 34, v155
	v_subrev_u32_e32 v37, 20, v155
	v_cndmask_b32_e32 v72, v210, v36, vcc
	v_cmp_gt_u32_e32 vcc, s10, v34
	v_add_u32_e32 v34, -5, v155
	v_subrev_u32_e32 v36, 48, v155
	v_cndmask_b32_e32 v50, v210, v53, vcc
	v_cmp_gt_u32_e32 vcc, s10, v35
	v_add_u32_e32 v35, -4, v155
	s_nop 0
	v_cndmask_b32_e32 v66, v210, v52, vcc
	v_cmp_gt_u32_e32 vcc, s10, v34
	v_subrev_u32_e32 v34, 37, v155
	s_nop 0
	v_cndmask_b32_e32 v70, v210, v39, vcc
	v_cmp_gt_u32_e32 vcc, s10, v35
	v_subrev_u32_e32 v35, 36, v155
	s_nop 0
	v_cndmask_b32_e32 v73, v210, v38, vcc
	v_cmp_gt_u32_e32 vcc, s10, v34
	v_add_u32_e32 v34, -7, v155
	s_nop 0
	v_cndmask_b32_e32 v52, v210, v55, vcc
	v_cmp_gt_u32_e32 vcc, s10, v35
	v_add_u32_e32 v35, -6, v155
	s_nop 0
	v_cndmask_b32_e32 v54, v210, v54, vcc
	v_cmp_gt_u32_e32 vcc, s10, v34
	v_subrev_u32_e32 v34, 39, v155
	s_nop 0
	v_cndmask_b32_e32 v71, v210, v41, vcc
	v_cmp_gt_u32_e32 vcc, s10, v35
	v_subrev_u32_e32 v35, 38, v155
	s_nop 0
	v_cndmask_b32_e32 v74, v210, v40, vcc
	v_cmp_gt_u32_e32 vcc, s10, v34
	v_add_u32_e32 v34, -16, v155
	v_subrev_u32_e32 v40, 22, v155
	v_cndmask_b32_e32 v53, v210, v57, vcc
	v_cmp_gt_u32_e32 vcc, s10, v35
	v_subrev_u32_e32 v35, 17, v155
	s_nop 0
	v_cndmask_b32_e32 v55, v210, v56, vcc
	v_cmp_gt_u32_e32 vcc, s10, v35
	s_nop 1
	v_cndmask_b32_e32 v43, v210, v43, vcc
	v_cmp_gt_u32_e32 vcc, s10, v34
	v_subrev_u32_e32 v34, 49, v155
	s_nop 0
	v_cndmask_b32_e32 v57, v210, v42, vcc
	v_cmp_gt_u32_e32 vcc, s10, v34
	v_subrev_u32_e32 v34, 19, v155
	s_nop 0
	v_cndmask_b32_e32 v35, v210, v59, vcc
	v_cmp_gt_u32_e32 vcc, s10, v36
	v_subrev_u32_e32 v36, 18, v155
	s_nop 0
	v_cndmask_b32_e32 v41, v210, v58, vcc
	v_cmp_gt_u32_e32 vcc, s10, v34
	v_subrev_u32_e32 v34, 51, v155
	s_nop 0
	v_cndmask_b32_e32 v42, v210, v45, vcc
	v_cmp_gt_u32_e32 vcc, s10, v36
	v_subrev_u32_e32 v36, 50, v155
	s_nop 0
	v_cndmask_b32_e32 v56, v210, v44, vcc
	v_cmp_gt_u32_e32 vcc, s10, v34
	s_nop 1
	v_cndmask_b32_e32 v34, v210, v61, vcc
	v_cmp_gt_u32_e32 vcc, s10, v36
	v_subrev_u32_e32 v36, 21, v155
	s_nop 0
	v_cndmask_b32_e32 v38, v210, v60, vcc
	v_cmp_gt_u32_e32 vcc, s10, v36
	v_subrev_u32_e32 v36, 53, v155
	s_nop 0
	v_cndmask_b32_e32 v44, v210, v47, vcc
	v_cmp_gt_u32_e32 vcc, s10, v37
	v_subrev_u32_e32 v37, 52, v155
	s_nop 0
	v_cndmask_b32_e32 v46, v210, v46, vcc
	v_cmp_gt_u32_e32 vcc, s10, v36
	s_nop 1
	v_cndmask_b32_e32 v36, v210, v63, vcc
	v_cmp_gt_u32_e32 vcc, s10, v37
	v_subrev_u32_e32 v37, 23, v155
	s_nop 0
	v_cndmask_b32_e32 v39, v210, v62, vcc
	v_cmp_gt_u32_e32 vcc, s10, v37
	v_subrev_u32_e32 v37, 55, v155
	s_nop 0
	v_cndmask_b32_e32 v45, v210, v49, vcc
	v_cmp_gt_u32_e32 vcc, s10, v40
	v_max_f32_e32 v49, v45, v45
	v_subrev_u32_e32 v40, 54, v155
	v_cndmask_b32_e32 v47, v210, v48, vcc
	v_cmp_gt_u32_e32 vcc, s10, v37
	s_nop 1
	v_cndmask_b32_e32 v37, v210, v65, vcc
	v_max_f32_e32 v48, v37, v37
	v_min_f32_e32 v48, v49, v48
	v_max3_f32 v49, v48, v75, v67
	v_max3_f32 v48, v48, v68, v51
	v_cmp_gt_u32_e32 vcc, s10, v40
	v_max3_f32 v49, v49, v72, v66
	v_max3_f32 v48, v48, v69, v50
	s_nop 0
	v_max3_f32 v49, v49, v73, v54
	v_max3_f32 v48, v48, v70, v52
	s_nop 0
	v_cndmask_b32_e32 v40, v210, v64, vcc
	v_max3_f32 v49, v49, v74, v55
	v_max3_f32 v48, v48, v71, v53
	s_nop 0
	v_max3_f32 v49, v49, v57, v41
	v_max3_f32 v48, v48, v43, v35
	s_nop 0
	v_max3_f32 v49, v49, v56, v38
	v_max3_f32 v48, v48, v42, v34
	s_nop 0
	v_max3_f32 v49, v49, v46, v39
	v_max3_f32 v48, v48, v44, v36
	s_nop 0
	v_max3_f32 v49, v49, v47, v40
	v_max3_f32 v48, v48, v45, v37
	s_nop 0
	v_max_f32_e32 v48, v48, v48
	v_max_f32_e32 v49, v49, v49
	v_max_f32_e32 v48, v49, v48
	ds_bpermute_b32 v49, v149, v48
	s_waitcnt lgkmcnt(0)
	v_max_f32_e32 v49, v49, v49
	v_max_f32_e32 v48, v48, v49
	v_cmp_lt_f32_e64 s[28:29], s2, v48
	s_mov_b32 s2, 0x41000000
	v_cmp_lt_f32_e32 vcc, s2, v48
	s_mov_b32 s2, 0xc1000000
	v_cmp_gt_f32_e64 s[2:3], s2, v48
	s_and_b64 s[2:3], s[2:3], s[28:29]
	s_andn2_b64 s[2:3], s[2:3], s[24:25]
	s_or_b64 s[2:3], s[2:3], vcc
	s_and_b64 vcc, exec, s[2:3]
	s_cbranch_vccnz .LBB0_596

; #define LAS __attribute__((address_space(3)))
; DI void cmpwin_unit(const Params& P, lptr L, int u, int tid, int lane, int wid) {
;     ...
;         float l = rs.l; l += __shfl_xor(l, 32);
;         const float sc = gwn / fmaxf(l, 1e-30f);
;         float* prow = PART + row * 512 + head * 64;
;         if ((PROBE_SUB & 4) && rp_ == 0) continue;
; #pragma unroll
;         for (int g4 = 0; g4 < 4; ++g4) {
;             f32x4 a = *(f32x4*)(prow + 8 * g4 + 4 * hi), c = *(f32x4*)(prow + 32 + 8 * g4 + 4 * hi);
;             a = a + (f32x4){o0[4 * g4] * sc, o0[4 * g4 + 1] * sc, o0[4 * g4 + 2] * sc, o0[4 * g4 + 3] * sc};
;             c = c + (f32x4){o1[4 * g4] * sc, o1[4 * g4 + 1] * sc, o1[4 * g4 + 2] * sc, o1[4 * g4 + 3] * sc};
;             *(f32x4*)(prow + 8 * g4 + 4 * hi) = a; *(f32x4*)(prow + 32 + 8 * g4 + 4 * hi) = c;
;         }
; DI void slc_unit(const Params& P, lptr L, int u, int tid, int lane, int wid) {
;     ...
;     LAS unsigned* sm = (LAS unsigned*)(L + AL_SM);
;     LAS unsigned* un = (LAS unsigned*)(L + AL_MISC);
;     LAS unsigned char* list = (LAS unsigned char*)(L + AL_LIST);
;     if (tid < 16) un[tid] = 0u;
;     __syncthreads();
;     { const unsigned w = sm[tid]; if (w) __hip_atomic_fetch_or(un + (tid & 7), w, __ATOMIC_RELAXED, __HIP_MEMORY_SCOPE_WORKGROUP); }
;     __syncthreads();
;     if (tid < 256) {
;         const unsigned w = un[tid >> 5];
;         if ((w >> (tid & 31)) & 1u) {
;             int pos = __popc(w & ((1u << (tid & 31)) - 1u));
;             for (int k = 0; k < (tid >> 5); ++k) pos += __popc(un[k]);
;             list[pos] = (unsigned char)tid;
;         }
;     }
.LBB0_598:
	global_load_dwordx4 v[12:15], v[158:159], off
	global_load_dwordx4 v[16:19], v[158:159], off offset:128
	global_load_dwordx4 v[20:23], v[158:159], off offset:32
	global_load_dwordx4 v[24:27], v[158:159], off offset:160
	global_load_dwordx4 v[28:31], v[158:159], off offset:64
	global_load_dwordx4 v[228:231], v[158:159], off offset:192
	global_load_dwordx4 v[232:235], v[158:159], off offset:96
	global_load_dwordx4 v[236:239], v[158:159], off offset:224
	v_lshlrev_b32_e32 v2, 16, v153
	v_mul_f32_e32 v2, 0xbfb8aa3b, v2
	v_exp_f32_e32 v2, v2
	v_readlane_b32 s75, v250, 34
	s_mov_b32 s64, s36
	s_mov_b32 s65, s37
	v_add_f32_e32 v2, 1.0, v2
	v_div_scale_f32 v3, s[2:3], v2, v2, 1.0
	v_rcp_f32_e32 v4, v3
	s_mov_b32 s74, s38
	s_mov_b32 s81, s40
	v_fma_f32 v5, -v3, v4, 1.0
	v_fmac_f32_e32 v4, v5, v4
	v_div_scale_f32 v5, vcc, 1.0, v2, 1.0
	v_mul_f32_e32 v6, v5, v4
	v_fma_f32 v7, -v3, v6, v5
	v_fmac_f32_e32 v6, v7, v4
	v_fma_f32 v3, -v3, v6, v5
	v_div_fmas_f32 v3, v3, v4, v6
	v_div_fixup_f32 v2, v3, v2, 1.0
	ds_bpermute_b32 v3, v149, v163
	s_waitcnt lgkmcnt(0)
	v_add_f32_e32 v3, v163, v3
	v_max_f32_e32 v3, 0xda24260, v3
	v_div_scale_f32 v4, s[2:3], v3, v3, v2
	v_rcp_f32_e32 v5, v4
	s_nop 0
	v_fma_f32 v6, -v4, v5, 1.0
	v_fmac_f32_e32 v5, v6, v5
	v_div_scale_f32 v6, vcc, v2, v3, v2
	v_mul_f32_e32 v7, v6, v5
	v_fma_f32 v8, -v4, v7, v6
	v_fmac_f32_e32 v7, v8, v5
	v_fma_f32 v4, -v4, v7, v6
	v_div_fmas_f32 v4, v4, v5, v7
	v_div_fixup_f32 v2, v4, v3, v2
	s_waitcnt vmcnt(6)
	v_pk_fma_f32 v[14:15], v[36:37], v[2:3], v[14:15] op_sel_hi:[1,0,1]
	v_pk_fma_f32 v[12:13], v[34:35], v[2:3], v[12:13] op_sel_hi:[1,0,1]
	v_pk_fma_f32 v[18:19], v[52:53], v[2:3], v[18:19] op_sel_hi:[1,0,1]
	v_pk_fma_f32 v[16:17], v[50:51], v[2:3], v[16:17] op_sel_hi:[1,0,1]
	global_store_dwordx4 v[158:159], v[12:15], off
	global_store_dwordx4 v[158:159], v[16:19], off offset:128
	s_waitcnt vmcnt(6)
	v_pk_fma_f32 v[22:23], v[40:41], v[2:3], v[22:23] op_sel_hi:[1,0,1]
	v_pk_fma_f32 v[20:21], v[38:39], v[2:3], v[20:21] op_sel_hi:[1,0,1]
	v_pk_fma_f32 v[26:27], v[56:57], v[2:3], v[26:27] op_sel_hi:[1,0,1]
	v_pk_fma_f32 v[24:25], v[54:55], v[2:3], v[24:25] op_sel_hi:[1,0,1]
	global_store_dwordx4 v[158:159], v[20:23], off offset:32
	global_store_dwordx4 v[158:159], v[24:27], off offset:160
	s_waitcnt vmcnt(6)
	v_pk_fma_f32 v[30:31], v[44:45], v[2:3], v[30:31] op_sel_hi:[1,0,1]
	v_pk_fma_f32 v[28:29], v[42:43], v[2:3], v[28:29] op_sel_hi:[1,0,1]
	v_pk_fma_f32 v[230:231], v[60:61], v[2:3], v[230:231] op_sel_hi:[1,0,1]
	v_pk_fma_f32 v[228:229], v[58:59], v[2:3], v[228:229] op_sel_hi:[1,0,1]
	global_store_dwordx4 v[158:159], v[28:31], off offset:64
	global_store_dwordx4 v[158:159], v[228:231], off offset:192
	s_waitcnt vmcnt(6)
	v_pk_fma_f32 v[234:235], v[48:49], v[2:3], v[234:235] op_sel_hi:[1,0,1]
	v_pk_fma_f32 v[232:233], v[46:47], v[2:3], v[232:233] op_sel_hi:[1,0,1]
	v_pk_fma_f32 v[238:239], v[64:65], v[2:3], v[238:239] op_sel_hi:[1,0,1]
	v_pk_fma_f32 v[236:237], v[62:63], v[2:3], v[236:237] op_sel_hi:[1,0,1]
	global_store_dwordx4 v[158:159], v[232:235], off offset:96
	global_store_dwordx4 v[158:159], v[236:239], off offset:224
	s_mov_b64 s[2:3], exec
	v_readlane_b32 s22, v250, 25
	v_readlane_b32 s23, v250, 26
	s_and_b64 s[22:23], s[2:3], s[22:23]
	s_mov_b64 exec, s[22:23]
	ds_write_b32 v129, v1 offset:37376
	s_or_b64 exec, exec, s[2:3]
	s_waitcnt lgkmcnt(0)
	s_barrier
	ds_read_b32 v2, v180
	s_waitcnt lgkmcnt(0)
	v_cmp_ne_u32_e32 vcc, 0, v2
	s_and_saveexec_b64 s[2:3], vcc
	ds_or_b32 v181, v2 offset:37376
	s_or_b64 exec, exec, s[2:3]
	s_waitcnt lgkmcnt(0)
	s_barrier
	s_mov_b64 s[2:3], exec
	v_readlane_b32 s22, v250, 14
	v_readlane_b32 s23, v250, 15
	s_and_b64 s[22:23], s[2:3], s[22:23]
	s_mov_b64 exec, s[22:23]
	s_cbranch_execz .LBB0_609
	ds_read_b32 v2, v183 offset:37376
	s_waitcnt lgkmcnt(0)
	v_and_b32_e32 v3, v2, v184
	v_cmp_ne_u32_e32 vcc, 0, v3
	s_and_b64 exec, exec, vcc
	s_cbranch_execz .LBB0_609
	v_and_b32_e32 v2, v2, v185
	v_bcnt_u32_b32 v2, v2, 0
	s_mov_b64 s[22:23], exec
	v_readlane_b32 s24, v250, 27
	v_readlane_b32 s25, v250, 28
	s_and_b64 s[24:25], s[22:23], s[24:25]
	s_mov_b64 exec, s[24:25]
	s_cbranch_execz .LBB0_608
	s_mov_b64 s[24:25], 0
	v_mov_b32_e32 v3, v182
	v_readlane_b32 s26, v250, 18

; DI float max3_asm(float a, float b, float c) { float r; asm("v_max3_f32 %0, %1, %2, %3" : "=v"(r) : "v"(a), "v"(b), "v"(c)); return r; }
; template <bool MASK>
; DI float mask_rowmax(f32x16& s0, f32x16& s1, const TP& tp) {
;     ...
;     const float seed = __builtin_fminf(s0[15], s1[15]);
;     float ma = seed, mb = seed;
; #pragma unroll
;     for (int r = 0; r < 16; r += 2) { ma = max3_asm(ma, s0[r], s1[r]); mb = max3_asm(mb, s0[r + 1], s1[r + 1]); }
;     const float mx = fmaxf(ma, mb);
;     return fmaxf(mx, __shfl_xor(mx, 32));
; }
; template <int MODE, bool MASK, bool WITH_O>
; DI void attn_tile_t(lptr Kt, lptr Vt, const bf16x8 (&qf)[4], f32x16& o0, f32x16& o1, RowState& rs, const TP& tp, int lane) {
;     const int hi = lane >> 5;
;     f32x16 s0, s1;
;     bias_init<MODE>(s0, s1, tp, tp.fb - rs.mref, hi);
;     qk_acc(Kt, qf, s0, s1, lane);
;     const float mx = mask_rowmax<MASK>(s0, s1, tp);
;     const bool was = rs.seen; rs.seen = was || (mx > -1e29f);
;     const bool trig = (mx > 8.f) || (!was && mx > -1e29f && mx < -8.f);
;     if (__builtin_expect(__any(trig), 0)) {
.Lslc_join:
	v_max_f32_e32 v49, v40, v40
	v_max_f32_e32 v57, v48, v48
	v_min_f32_e32 v49, v57, v49
	v_max3_f32 v57, v49, v106, v102
	v_max3_f32 v49, v49, v103, v51
	s_mov_b32 s0, 0xefa18f08
	v_max3_f32 v57, v57, v104, v50
	v_max3_f32 v49, v49, v105, v52
	s_nop 0
	v_max3_f32 v57, v57, v107, v53
	v_max3_f32 v49, v49, v108, v54
	s_nop 0
	v_max3_f32 v57, v57, v109, v55
	v_max3_f32 v49, v49, v110, v41
	s_nop 0
	v_max3_f32 v57, v57, v56, v38
	v_max3_f32 v49, v49, v43, v34
	s_nop 0
	v_max3_f32 v57, v57, v42, v0
	v_max3_f32 v49, v49, v44, v35
	s_nop 0
	v_max3_f32 v57, v57, v45, v36
	v_max3_f32 v49, v49, v46, v37
	s_nop 0
	v_max3_f32 v57, v57, v47, v39
	v_max3_f32 v49, v49, v48, v40
	s_nop 0
	v_max_f32_e32 v49, v49, v49
	v_max_f32_e32 v57, v57, v57
	v_max_f32_e32 v49, v57, v49
	ds_bpermute_b32 v57, v149, v49
	s_waitcnt lgkmcnt(0)
	v_max_f32_e32 v57, v57, v57
	v_max_f32_e32 v49, v49, v57
	v_cmp_lt_f32_e64 s[28:29], s0, v49
	s_mov_b32 s0, 0x41000000
	v_cmp_lt_f32_e32 vcc, s0, v49
	s_mov_b32 s0, 0xc1000000
	v_cmp_gt_f32_e64 s[0:1], s0, v49
	s_and_b64 s[0:1], s[0:1], s[28:29]
	s_andn2_b64 s[0:1], s[0:1], s[22:23]
	s_or_b64 s[0:1], s[0:1], vcc
	s_and_b64 vcc, exec, s[0:1]
	s_cbranch_vccnz .LBB0_622

; DI unsigned pk_bf16(float lo, float hi) { f32x2 v = {lo, hi}; bf16x2_t b = __builtin_convertvector(v, bf16x2_t); return __builtin_bit_cast(unsigned, b); }
; DI void slc_unit(const Params& P, lptr L, int u, int tid, int lane, int wid) {
;     ...
;     float l = rs.l; l += __shfl_xor(l, 32);
;     const float sc = gs / fmaxf(l, 1e-30f);
;     const float* prow = PART + row * 512 + head * 64;
;     bf16_t* orow = ATT + row * DM + 512 + head * 64;
; #pragma unroll
;     for (int g4 = 0; g4 < 4; ++g4) {
;         const f32x4 a = *(const f32x4*)(prow + 8 * g4 + 4 * hi), c = *(const f32x4*)(prow + 32 + 8 * g4 + 4 * hi);
;         u32x2 w0, w1;
;         w0.x = pk_bf16(a[0] + o0[4 * g4] * sc, a[1] + o0[4 * g4 + 1] * sc); w0.y = pk_bf16(a[2] + o0[4 * g4 + 2] * sc, a[3] + o0[4 * g4 + 3] * sc);
;         w1.x = pk_bf16(c[0] + o1[4 * g4] * sc, c[1] + o1[4 * g4 + 1] * sc); w1.y = pk_bf16(c[2] + o1[4 * g4 + 2] * sc, c[3] + o1[4 * g4 + 3] * sc);
;         *(u32x2*)(orow + 8 * g4 + 4 * hi) = w0; *(u32x2*)(orow + 32 + 8 * g4 + 4 * hi) = w1;
;     }
.LBB0_624:
	v_mov_b32_e32 v91, v1
	v_mov_b32_e32 v155, v1
	s_mov_b32 s61, s83
	v_readlane_b32 s0, v250, 0
	v_readlane_b32 s1, v250, 1
	v_lshlrev_b64 v[62:63], 11, v[90:91]
	s_nop 0
	v_lshl_add_u64 v[62:63], s[0:1], 0, v[62:63]
	v_lshl_add_u64 v[62:63], v[62:63], 0, s[60:61]
	v_lshl_add_u64 v[62:63], v[62:63], 0, v[154:155]
	global_load_dwordx4 v[228:231], v[62:63], off
	global_load_dwordx4 v[232:235], v[62:63], off offset:128
	global_load_dwordx4 v[236:239], v[62:63], off offset:32
	global_load_dwordx4 v[240:243], v[62:63], off offset:160
	global_load_dwordx4 v[244:247], v[62:63], off offset:64
	global_load_dwordx4 v[50:53], v[62:63], off offset:192
	global_load_dwordx4 v[54:57], v[62:63], off offset:96
	global_load_dwordx4 v[58:61], v[62:63], off offset:224
	v_lshlrev_b32_e32 v0, 16, v98
	v_mul_f32_e32 v0, 0xbfb8aa3b, v0
	v_exp_f32_e32 v0, v0
	v_mov_b32_e32 v91, v1
	s_mov_b32 s61, s83
	v_mov_b32_e32 v155, v1
	v_add_f32_e32 v0, 1.0, v0
	v_div_scale_f32 v34, s[0:1], v0, v0, 1.0
	v_rcp_f32_e32 v35, v34
	s_nop 0
	v_fma_f32 v36, -v34, v35, 1.0
	v_fmac_f32_e32 v35, v36, v35
	v_div_scale_f32 v36, vcc, 1.0, v0, 1.0
	v_mul_f32_e32 v37, v36, v35
	v_fma_f32 v38, -v34, v37, v36
	v_fmac_f32_e32 v37, v38, v35
	v_fma_f32 v34, -v34, v37, v36
	v_div_fmas_f32 v34, v34, v35, v37
	v_div_fixup_f32 v0, v34, v0, 1.0
	ds_bpermute_b32 v34, v149, v100
	s_waitcnt lgkmcnt(0)
	v_add_f32_e32 v34, v100, v34
	v_max_f32_e32 v34, 0xda24260, v34
	v_div_scale_f32 v35, s[0:1], v34, v34, v0
	v_rcp_f32_e32 v36, v35
	v_readlane_b32 s0, v250, 0
	v_readlane_b32 s1, v250, 1
	v_fma_f32 v37, -v35, v36, 1.0
	v_fmac_f32_e32 v36, v37, v36
	v_div_scale_f32 v37, vcc, v0, v34, v0
	v_mul_f32_e32 v38, v37, v36
	v_fma_f32 v39, -v35, v38, v37
	v_fmac_f32_e32 v38, v39, v36
	v_fma_f32 v35, -v35, v38, v37
	v_div_fmas_f32 v35, v35, v36, v38
	v_lshlrev_b64 v[36:37], 11, v[90:91]
	v_lshl_add_u64 v[38:39], s[0:1], 0, v[36:37]
	v_lshl_add_u64 v[38:39], v[38:39], 0, s[60:61]
	v_lshl_add_u64 v[46:47], v[38:39], 0, v[154:155]
	v_lshl_add_u64 v[36:37], s[34:35], 0, v[36:37]
	v_div_fixup_f32 v34, v35, v34, v0
	v_lshl_add_u64 v[36:37], v[36:37], 0, s[82:83]
	v_lshlrev_b32_e32 v0, 1, v134
	v_lshl_add_u64 v[48:49], v[36:37], 0, v[0:1]
	s_mov_b64 s[0:1], 0x3800400
	v_lshl_add_u64 v[36:37], v[48:49], 0, s[0:1]
	s_mov_b32 s0, 0x3800000
	s_waitcnt vmcnt(7)
	v_pk_fma_f32 v[18:19], v[18:19], v[34:35], v[228:229] op_sel_hi:[1,0,1]
	s_waitcnt vmcnt(6)
	v_pk_fma_f32 v[2:3], v[2:3], v[34:35], v[232:233] op_sel_hi:[1,0,1]
	v_pk_fma_f32 v[4:5], v[4:5], v[34:35], v[234:235] op_sel_hi:[1,0,1]
	v_pk_fma_f32 v[20:21], v[20:21], v[34:35], v[230:231] op_sel_hi:[1,0,1]
	v_cvt_pk_bf16_f32 v2, v2, v3
	v_cvt_pk_bf16_f32 v3, v4, v5
	v_add_co_u32_e32 v4, vcc, s0, v48
	v_cvt_pk_bf16_f32 v18, v18, v19
	v_cvt_pk_bf16_f32 v19, v20, v21
	v_addc_co_u32_e32 v5, vcc, 0, v49, vcc
	global_store_dwordx2 v[4:5], v[18:19], off offset:1024
	global_store_dwordx2 v[36:37], v[2:3], off offset:64
	s_nop 0
	s_mov_b64 s[0:1], -1
	s_waitcnt vmcnt(7)
	v_pk_fma_f32 v[2:3], v[22:23], v[34:35], v[236:237] op_sel_hi:[1,0,1]
	v_pk_fma_f32 v[4:5], v[24:25], v[34:35], v[238:239] op_sel_hi:[1,0,1]
	v_cvt_pk_bf16_f32 v2, v2, v3
	v_cvt_pk_bf16_f32 v3, v4, v5
	s_waitcnt vmcnt(6)
	v_pk_fma_f32 v[4:5], v[6:7], v[34:35], v[240:241] op_sel_hi:[1,0,1]
	v_pk_fma_f32 v[6:7], v[8:9], v[34:35], v[242:243] op_sel_hi:[1,0,1]
	v_cvt_pk_bf16_f32 v4, v4, v5
	v_cvt_pk_bf16_f32 v5, v6, v7
	global_store_dwordx2 v[36:37], v[2:3], off offset:16
	global_store_dwordx2 v[36:37], v[4:5], off offset:80
	s_nop 0
	s_waitcnt vmcnt(7)
	v_pk_fma_f32 v[2:3], v[26:27], v[34:35], v[244:245] op_sel_hi:[1,0,1]
	v_pk_fma_f32 v[4:5], v[28:29], v[34:35], v[246:247] op_sel_hi:[1,0,1]
	v_cvt_pk_bf16_f32 v2, v2, v3
	v_cvt_pk_bf16_f32 v3, v4, v5
	s_waitcnt vmcnt(6)
	v_pk_fma_f32 v[4:5], v[10:11], v[34:35], v[50:51] op_sel_hi:[1,0,1]
	v_pk_fma_f32 v[6:7], v[12:13], v[34:35], v[52:53] op_sel_hi:[1,0,1]
	v_cvt_pk_bf16_f32 v4, v4, v5
	v_cvt_pk_bf16_f32 v5, v6, v7
	global_store_dwordx2 v[36:37], v[2:3], off offset:32
	global_store_dwordx2 v[36:37], v[4:5], off offset:96
	s_nop 0
	s_waitcnt vmcnt(7)
	v_pk_fma_f32 v[6:7], v[30:31], v[34:35], v[54:55] op_sel_hi:[1,0,1]
	v_pk_fma_f32 v[8:9], v[32:33], v[34:35], v[56:57] op_sel_hi:[1,0,1]
	v_cvt_pk_bf16_f32 v6, v6, v7
	v_cvt_pk_bf16_f32 v7, v8, v9
	s_waitcnt vmcnt(6)
	v_pk_fma_f32 v[2:3], v[14:15], v[34:35], v[58:59] op_sel_hi:[1,0,1]
	v_pk_fma_f32 v[4:5], v[16:17], v[34:35], v[60:61] op_sel_hi:[1,0,1]
	v_cvt_pk_bf16_f32 v2, v2, v3
	v_cvt_pk_bf16_f32 v3, v4, v5
	global_store_dwordx2 v[36:37], v[6:7], off offset:48
	global_store_dwordx2 v[36:37], v[2:3], off offset:112
